# MLA unit rewritten around v_mfma_f32_32x32x16_bf16: one query row per lane, half the MFMA instructions, one cross-lane max step
# baseline (speedup 1.0000x reference)
; #define LAS __attribute__((address_space(3)))
;     pg8::Gemm g{A, Bt, lda, ldb, M, N, K}; pg8::StaticOrder S; S.init(M, N, C.G, (((C.bid & 31) * 8 + (C.bid >> 5)) + crot) % C.G);
;     pg8::gemm_phase<pg8::Epi<MODE>, pg8::StaticOrder, true, true>(C.lds, g, S, E);
; __global__ void __launch_bounds__(512) mega_fwd(Params p) {
;     extern __shared__ __attribute__((aligned(16))) unsigned char lds_raw[];
;     cg::grid_group grid = cg::this_grid();
;     Ctx C; C.lds = (LAS unsigned char*)lds_raw; C.tid = threadIdx.x; C.lane = C.tid & 63; C.wave = __builtin_amdgcn_readfirstlane(C.tid >> 6); C.G = gridDim.x; C.bid = blockIdx.x;
;     unsigned char* ws = p.ws;
;     bf16* W = (bf16*)(ws + WS_W); bf16* H = (bf16*)(ws + WS_H); bf16* P = (bf16*)(ws + WS_P); bf16* Y = (bf16*)(ws + WS_Y);
;     bf16* QM = (bf16*)(ws + WS_QM); bf16* KM = (bf16*)(ws + WS_KM); bf16* VTM = (bf16*)(ws + WS_VTM); bf16* VTA = (bf16*)(ws + WS_VTA);
;     bf16* MG = (bf16*)(ws + WS_MG); bf16* GS = (bf16*)(ws + WS_GS); bf16* HID = (bf16*)(ws + WS_HID);
;     volatile LAS unsigned* xst = (volatile LAS unsigned*)(C.lds + RING_BYTES + 64);
;     if (threadIdx.x < 2) xst[threadIdx.x] = 0u;
;     __syncthreads();
;     XcdBarrier xbar = xcd_barrier_post((unsigned*)(p.ws), xst);
;     phase_tables(C, p);
;     asm volatile("s_waitcnt vmcnt(0) lgkmcnt(0)" ::: "memory"); grid.sync();
;     for (int l = 0; l < DEPTH; ++l) {
;         { int t_ = threadIdx.x; asm volatile("" : "+v"(t_)); C.tid = t_; C.lane = t_ & 63; C.wave = __builtin_amdgcn_readfirstlane(t_ >> 6); }
;         const float* xcur = (l == 0) ? p.x : p.out;
.LBB0_13:
	s_or_b64 exec, exec, s[0:1]
	v_lshrrev_b32_e32 v1, 20, v0
	v_lshrrev_b32_e32 v0, 10, v0
	s_waitcnt vmcnt(0) lgkmcnt(0)
	v_or_b32_e32 v0, v0, v1
	s_movk_i32 s0, 0x3ff
	v_and_or_b32 v0, v0, s0, v174
	v_cmp_eq_u32_e32 vcc, 0, v0
	s_barrier
	s_and_saveexec_b64 s[0:1], vcc
	s_branch .LBB0_23
.LBB0_23:
	s_or_b64 exec, exec, s[0:1]
	s_abs_i32 s4, s96
	v_cvt_f32_u32_e32 v0, s4
	v_readlane_b32 s20, v251, 0
	s_lshl_b32 s1, s20, 3
	v_writelane_b32 v251, s1, 28
	v_rcp_iflag_f32_e32 v0, v0
	s_and_b32 s11, s1, 0xf8
	s_sub_i32 s1, 0, s4
	s_ashr_i32 s0, s20, 5
	v_mul_f32_e32 v0, 0x4f7ffffe, v0
	v_cvt_u32_f32_e32 v0, v0
	s_add_i32 s11, s11, s0
	s_abs_i32 s2, s11
	s_ashr_i32 s0, s11, 31
	v_readfirstlane_b32 s9, v0
	s_mul_i32 s1, s1, s9
	s_mul_hi_u32 s1, s9, s1
	s_add_i32 s9, s9, s1
	s_mul_hi_u32 s1, s2, s9
	s_mul_i32 s1, s1, s4
	s_sub_i32 s1, s2, s1
	s_sub_i32 s2, s1, s4
	s_cmp_ge_u32 s1, s4
	s_cselect_b32 s1, s2, s1
	s_sub_i32 s2, s1, s4
	s_cmp_ge_u32 s1, s4
	s_cselect_b32 s1, s2, s1
	s_xor_b32 s1, s1, s0
	s_sub_i32 s61, s1, s0
	s_ashr_i32 s33, s61, 31
	s_lshr_b32 s0, s33, 29
	s_add_i32 s3, s61, s0
	s_and_b32 s0, s3, -8
	s_sub_i32 s8, s61, s0
	s_lshl_b32 s0, s8, 8
	s_mul_i32 s1, s8, 0x101
	s_cmp_lt_i32 s8, 0
	s_cselect_b32 s1, s1, s0
	s_lshl_b32 s0, s8, 6
	s_cmp_lt_i32 s8, 0
	s_mul_i32 s2, s8, 0x41
	s_cselect_b32 s2, s2, s0
	s_lshl_b32 s0, s8, 5
	s_cmp_lt_i32 s8, 0
	s_movk_i32 s5, 0x91
	s_cselect_b32 s12, s5, 0x90
	s_mul_i32 s5, s8, 33
	s_cselect_b32 s10, 49, 48
	s_cselect_b32 s0, s5, s0
	s_add_u32 s6, s18, 0x500000
	s_addc_u32 s7, s19, 0
	s_add_u32 s14, s18, 0x100000
	s_addc_u32 s15, s19, 0
	s_add_u32 s34, s18, 0x800000
	s_addc_u32 s35, s19, 0
	s_add_u32 s22, s18, 0x2900000
	s_addc_u32 s23, s19, 0
	s_add_u32 s24, s18, 0x6900000
	v_writelane_b32 v251, s14, 29
	s_addc_u32 s25, s19, 0
	s_mul_i32 s12, s8, s12
	v_writelane_b32 v251, s15, 30
	s_add_u32 s14, s18, 0xf900000
	s_addc_u32 s15, s19, 0
	s_add_u32 s28, s18, 0x15900000
	v_writelane_b32 v251, s14, 31
	s_addc_u32 s29, s19, 0
	s_mul_i32 s8, s8, s10
	v_writelane_b32 v251, s15, 32
	s_add_u32 s14, s18, 0x18900000
	s_addc_u32 s15, s19, 0
	v_writelane_b32 v251, s14, 33
	s_mov_b32 s89, 0
	s_barrier
	v_writelane_b32 v251, s15, 34
	s_add_u32 s14, s18, 0x1a900000
	s_addc_u32 s15, s19, 0
	v_writelane_b32 v251, s14, 35
	v_mov_b32_e32 v175, 0x358637bd
	s_nop 0
	v_writelane_b32 v251, s15, 36
	s_add_u32 s14, s18, 0x1c900000
	s_addc_u32 s15, s19, 0
	s_lshl_b32 s58, s96, 3
	s_add_u32 s36, s18, 0x2060000
	s_addc_u32 s37, s19, 0
	s_add_u32 s38, s18, 0x1860000
	s_addc_u32 s39, s19, 0
	s_add_u32 s40, s18, 0x1660000
	v_writelane_b32 v251, s14, 37
	s_addc_u32 s41, s19, 0
	s_add_u32 s5, s18, 0x1360000
	v_writelane_b32 v251, s15, 38
	v_writelane_b32 v251, s5, 39
	s_addc_u32 s5, s19, 0
	s_add_u32 s42, s18, 0x1280000
	s_addc_u32 s43, s19, 0
	s_add_u32 s14, s18, 0xc80000
	v_writelane_b32 v251, s5, 40
	s_addc_u32 s15, s19, 0
	v_writelane_b32 v251, s14, 41
	v_mov_b32_e32 v176, 0x260
	v_mov_b32_e32 v177, 1
	v_writelane_b32 v251, s15, 42
	s_add_u32 s14, s18, 0x200
	s_addc_u32 s15, s19, 0
	v_writelane_b32 v251, s14, 43
	v_mov_b32_e32 v179, 0x1200
	v_mov_b32_e32 v180, 0x80
	v_writelane_b32 v251, s15, 44
	s_add_u32 s14, s18, 0x1000
	s_addc_u32 s15, s19, 0
	v_writelane_b32 v251, s14, 45
	v_mov_b32_e32 v181, 0xf149f2ca
	v_mov_b64_e32 v[134:135], 0x180
	v_writelane_b32 v251, s15, 46
	s_add_u32 s14, s18, 0x1100
	s_addc_u32 s15, s19, 0
	v_writelane_b32 v251, s14, 47
	v_mov_b64_e32 v[136:137], 0x17f
	v_mov_b64_e32 v[138:139], 0x100
	v_writelane_b32 v251, s15, 48
	s_add_u32 s14, s18, 0x1200
	s_addc_u32 s15, s19, 0
	v_writelane_b32 v251, s14, 49
	v_mov_b64_e32 v[140:141], 0xff
	v_mov_b32_e32 v182, 0x600
	v_writelane_b32 v251, s15, 50
	s_add_u32 s14, s18, 0x1300
	s_addc_u32 s15, s19, 0
	v_writelane_b32 v251, s14, 51
	s_cmp_eq_u32 s27, 15
	v_mov_b32_e32 v183, 0x24000
	v_writelane_b32 v251, s15, 52
	s_cselect_b64 s[14:15], -1, 0
	v_writelane_b32 v251, s14, 53
	s_cmp_eq_u32 s27, 14
	v_mov_b32_e32 v184, 0x8000
	v_writelane_b32 v251, s15, 54
	s_cselect_b64 s[14:15], -1, 0
	v_writelane_b32 v251, s14, 55
	s_cmp_eq_u32 s27, 13
	v_mov_b64_e32 v[142:143], 0x200
	v_writelane_b32 v251, s15, 56
	s_cselect_b64 s[14:15], -1, 0
	v_writelane_b32 v251, s14, 57
	s_cmp_eq_u32 s27, 12
	v_mov_b64_e32 v[144:145], 0x1ff
	v_writelane_b32 v251, s15, 58
	s_cselect_b64 s[14:15], -1, 0
	v_writelane_b32 v251, s14, 59
	s_cmp_eq_u32 s27, 11
	v_mov_b64_e32 v[146:147], 0x800
	v_writelane_b32 v251, s15, 60
	s_cselect_b64 s[14:15], -1, 0
	v_writelane_b32 v251, s14, 61
	s_cmp_eq_u32 s27, 10
	v_mov_b64_e32 v[148:149], 0x7ff
	v_writelane_b32 v251, s15, 62
	s_cselect_b64 s[14:15], -1, 0
	v_writelane_b32 v251, s14, 63
	s_cmp_eq_u32 s27, 9
	s_movk_i32 s80, 0x7fff
	v_writelane_b32 v252, s15, 0
	s_cselect_b64 s[14:15], -1, 0
	v_writelane_b32 v252, s14, 1
	s_cmp_eq_u32 s27, 8
	s_mov_b32 s85, 0xffff0000
	v_writelane_b32 v252, s15, 2
	s_cselect_b64 s[14:15], -1, 0
	v_writelane_b32 v252, s14, 3
	s_cmp_eq_u32 s27, 7
	s_movk_i32 s82, 0xc00
	v_writelane_b32 v252, s15, 4
	s_cselect_b64 s[14:15], -1, 0
	v_writelane_b32 v252, s14, 5
	s_cmp_eq_u32 s27, 6
	s_movk_i32 s83, 0x5280
	v_writelane_b32 v252, s15, 6
	s_cselect_b64 s[14:15], -1, 0
	v_writelane_b32 v252, s14, 7
	s_cmp_eq_u32 s27, 5
	s_mov_b32 s84, 0xf800000
	v_writelane_b32 v252, s15, 8
	s_cselect_b64 s[14:15], -1, 0
	v_writelane_b32 v252, s14, 9
	s_cmp_eq_u32 s27, 4
	s_movk_i32 s86, 0x1200
	v_writelane_b32 v252, s15, 10
	s_cselect_b64 s[14:15], -1, 0
	v_writelane_b32 v252, s14, 11
	s_cmp_eq_u32 s27, 3
	s_mov_b32 s87, 0xfe03f81
	v_writelane_b32 v252, s15, 12
	s_cselect_b64 s[14:15], -1, 0
	v_writelane_b32 v252, s14, 13
	s_cmp_eq_u32 s27, 2
;     __host__ __device__ bool next(int i, Unit& u) const {
;         const long L = (long)i * G + c; if (L >= nwg) return false;
;         int wgid = (int)L; { const int q = nwg / NXCD, r = nwg % NXCD, xcd = wgid % NXCD, off = wgid / NXCD; wgid = (xcd < r ? xcd * (q + 1) : r * (q + 1) + (xcd - r) * q) + off; }
;         const int nig = WGM * nN, gid = wgid / nig, fm = gid * WGM, gsz = (nM - fm) < WGM ? (nM - fm) : WGM;
;         u.pm = fm + ((wgid % nig) % gsz); u.pn = (wgid % nig) / gsz; return true;
;     }
;     pg8::Gemm g{A, Bt, lda, ldb, M, N, K}; pg8::StaticOrder S; S.init(M, N, C.G, (((C.bid & 31) * 8 + (C.bid >> 5)) + crot) % C.G);
;     pg8::gemm_phase<pg8::Epi<MODE>, pg8::StaticOrder, true, true>(C.lds, g, S, E);
	s_movk_i32 s92, 0xff7f
	v_writelane_b32 v252, s15, 14
	s_cselect_b64 s[14:15], -1, 0
	v_writelane_b32 v252, s14, 15
	s_cmp_eq_u32 s27, 1
	s_mov_b32 s60, 0x3e16c740
	v_writelane_b32 v252, s15, 16
	s_cselect_b64 s[14:15], -1, 0
	v_writelane_b32 v252, s14, 17
	s_cmp_eq_u32 s27, 0
	s_nop 0
	v_writelane_b32 v252, s15, 18
	s_cselect_b64 s[14:15], -1, 0
	s_lshl_b32 s5, s27, 8
	s_add_u32 s5, s18, s5
	v_writelane_b32 v252, s14, 19
	s_addc_u32 s13, s19, 0
	s_nop 0
	v_writelane_b32 v252, s15, 20
	s_add_u32 s14, s5, 0x1400
	s_addc_u32 s15, s13, 0
	v_writelane_b32 v252, s14, 21
	s_nop 1
	v_writelane_b32 v252, s15, 22
	s_add_u32 s14, s5, 0x2400
	s_addc_u32 s15, s13, 0
	v_writelane_b32 v252, s14, 23
	s_nop 1
	v_writelane_b32 v252, s15, 24
	s_add_u32 s14, s18, 0x3400
	s_addc_u32 s15, s19, 0
	v_writelane_b32 v252, s14, 25
	s_nop 1
	v_writelane_b32 v252, s15, 26
	s_add_u32 s14, s18, 0x3500
	s_addc_u32 s15, s19, 0
	v_writelane_b32 v252, s14, 27
	s_ashr_i32 s5, s96, 31
	s_add_u32 s13, s18, 0x940000
	v_writelane_b32 v252, s15, 28
	v_writelane_b32 v252, s13, 29
	s_addc_u32 s13, s19, 0
	v_writelane_b32 v252, s13, 30
	s_lshr_b32 s13, s96, 31
	s_add_i32 s13, s96, s13
	s_ashr_i32 s13, s13, 1
	s_add_i32 s11, s11, s13
	s_cmpk_lt_i32 s20, 0x100
	s_cselect_b64 s[14:15], -1, 0
	v_writelane_b32 v252, s14, 31
	s_cmpk_lt_i32 s20, 0x400
	s_nop 0
	v_writelane_b32 v252, s15, 32
	s_cselect_b64 s[14:15], -1, 0
	v_writelane_b32 v252, s14, 33
	s_nop 1
	v_writelane_b32 v252, s15, 34
	s_add_u32 s14, s18, 0x11900000
	s_addc_u32 s15, s19, 0
	s_add_u32 s21, s18, 0x6900e00
	s_addc_u32 s27, s19, 0
	s_add_u32 s31, s18, 0x6901000
	s_addc_u32 s44, s19, 0
	s_add_u32 s45, s18, 0x12e0000
	s_addc_u32 s46, s19, 0
	s_add_u32 s47, s18, 0x1320000
	v_writelane_b32 v252, s14, 35
	s_addc_u32 s48, s19, 0
	s_nop 0
	v_writelane_b32 v252, s15, 36
	s_add_u32 s14, s18, 0x13900000
	s_addc_u32 s15, s19, 0
	v_writelane_b32 v252, s14, 37
	s_cmpk_lt_i32 s61, 0x480
	s_nop 0
	v_writelane_b32 v252, s15, 38
	s_cselect_b64 s[14:15], -1, 0
	s_ashr_i32 s3, s3, 3
	s_add_i32 s12, s12, s3
	v_writelane_b32 v252, s14, 39
	s_mul_hi_i32 s13, s12, 0x38e38e39
	s_nop 0
	v_writelane_b32 v252, s15, 40
	s_lshr_b32 s14, s13, 31
	s_ashr_i32 s13, s13, 4
	s_add_i32 s13, s13, s14
	s_mul_i32 s14, s13, 0x48
	s_sub_i32 s12, s12, s14
	s_bfe_i32 s14, s12, 0x80000
	s_bfe_u32 s14, s14, 0x3000c
	s_add_i32 s14, s12, s14
	s_and_b32 s15, s14, 0xf8
	s_sub_i32 s12, s12, s15
	s_bfe_i32 s14, s14, 0x80000
	s_lshl_b32 s13, s13, 3
	s_sext_i32_i16 s14, s14
	s_sext_i32_i8 s12, s12
	s_add_i32 s50, s13, s12
	s_ashr_i32 s12, s14, 3
	v_writelane_b32 v252, s12, 41
	s_lshr_b32 s12, s14, 3
	s_mov_b32 s14, s50
	s_ashr_i32 s51, s50, 31
	s_bfe_i64 s[12:13], s[12:13], 0x100000
	v_writelane_b32 v252, s14, 42
	s_lshl_b64 s[12:13], s[12:13], 19
	s_nop 0
	v_writelane_b32 v252, s15, 43
	s_lshl_b64 s[14:15], s[50:51], 19
	s_add_u32 s12, s34, s12
	v_writelane_b32 v252, s34, 44
	s_addc_u32 s13, s35, s13
	s_nop 0
	v_writelane_b32 v252, s35, 45
	s_add_u32 s34, s12, 0x40000
	s_addc_u32 s35, s13, 0
	v_writelane_b32 v252, s34, 46
	s_add_u32 s14, s22, s14
	s_addc_u32 s15, s23, s15
	v_writelane_b32 v252, s35, 47
	s_add_u32 s34, s14, 0x40000
	v_writelane_b32 v252, s14, 48
	s_addc_u32 s35, s15, 0
	s_nop 0
	v_writelane_b32 v252, s15, 49
	v_writelane_b32 v252, s34, 50
	s_add_u32 s14, s12, 0x40080
	s_nop 0
	v_writelane_b32 v252, s35, 51
	v_writelane_b32 v252, s12, 52
	s_addc_u32 s15, s13, 0
	s_nop 0
	v_writelane_b32 v252, s13, 53
	s_abs_i32 s12, s11
	s_mul_hi_u32 s9, s12, s9
	s_mul_i32 s9, s9, s4
	s_sub_i32 s9, s12, s9
	s_ashr_i32 s11, s11, 31
	s_sub_i32 s12, s9, s4
	s_cmp_ge_u32 s9, s4
	s_cselect_b32 s9, s12, s9
	s_sub_i32 s12, s9, s4
	s_cmp_ge_u32 s9, s4
	s_cselect_b32 s4, s12, s9
	s_xor_b32 s4, s4, s11
	s_sub_i32 s9, s4, s11
	v_writelane_b32 v252, s14, 54
	s_cmpk_lt_i32 s9, 0x80
	s_cselect_b64 s[10:11], -1, 0
	v_writelane_b32 v252, s15, 55
	v_writelane_b32 v252, s10, 56
	s_ashr_i32 s4, s9, 31
	s_nop 0
	v_writelane_b32 v252, s11, 57
	v_writelane_b32 v252, s4, 58
	s_lshr_b32 s4, s4, 29
	s_add_i32 s4, s9, s4
	s_ashr_i32 s10, s4, 3
	s_and_b32 s4, s4, -8
	s_sub_i32 s4, s9, s4
	v_writelane_b32 v252, s10, 59
	s_cmp_gt_i32 s4, -1
	v_writelane_b32 v252, s9, 60
	s_cselect_b64 s[10:11], -1, 0
	s_lshl_b32 s9, s4, 4
	v_writelane_b32 v252, s10, 61
	s_cmpk_lt_i32 s61, 0x180
	s_nop 0
	v_writelane_b32 v252, s11, 62
	s_cselect_b64 s[10:11], -1, 0
	v_writelane_b32 v253, s10, 0
	s_cmpk_lt_i32 s61, 0x100
	v_writelane_b32 v252, s9, 63
	v_writelane_b32 v253, s11, 1
	s_cselect_b64 s[10:11], -1, 0
	s_add_i32 s8, s8, s3
	v_writelane_b32 v253, s10, 2
	s_mul_hi_i32 s9, s8, 0x2aaaaaab
	s_nop 0
	v_writelane_b32 v253, s11, 3
	s_lshr_b32 s10, s9, 31
	s_ashr_i32 s9, s9, 2
	s_add_i32 s9, s9, s10
	s_mul_i32 s10, s9, 24
	s_sub_i32 s8, s8, s10
	s_bfe_i32 s10, s8, 0x80000
	s_bfe_u32 s10, s10, 0x3000c
	s_add_i32 s10, s8, s10
	s_and_b32 s11, s10, 0xf8
	s_sub_i32 s8, s8, s11
	s_lshl_b32 s9, s9, 3
	s_sext_i32_i8 s8, s8
	s_add_i32 s11, s9, s8
	s_bfe_i32 s8, s10, 0x80000
	s_sext_i32_i16 s8, s8
	s_ashr_i32 s9, s8, 3
	s_lshr_b32 s8, s8, 3
	v_writelane_b32 v253, s9, 4
	s_bfe_i64 s[8:9], s[8:9], 0x100000
	s_lshl_b64 s[8:9], s[8:9], 17
	s_add_u32 s12, s42, s8
	v_writelane_b32 v253, s42, 5
	s_addc_u32 s13, s43, s9
	s_add_u32 s8, s12, 0x10000
	v_writelane_b32 v253, s43, 6
	s_addc_u32 s9, s13, 0
	v_writelane_b32 v253, s8, 7
	s_nop 1
	v_writelane_b32 v253, s9, 8
	v_writelane_b32 v253, s11, 9
	s_mul_i32 s9, s11, 0x120000
	s_mul_hi_i32 s8, s11, 0x120000
	v_writelane_b32 v253, s21, 10
	s_add_u32 s10, s21, s9
	v_writelane_b32 v253, s27, 11
	s_addc_u32 s11, s27, s8
	s_add_u32 s8, s10, 0x90000
	v_writelane_b32 v253, s10, 12
;     __host__ __device__ bool next(int i, Unit& u) const {
;         const long L = (long)i * G + c; if (L >= nwg) return false;
;         int wgid = (int)L; { const int q = nwg / NXCD, r = nwg % NXCD, xcd = wgid % NXCD, off = wgid / NXCD; wgid = (xcd < r ? xcd * (q + 1) : r * (q + 1) + (xcd - r) * q) + off; }
;         const int nig = WGM * nN, gid = wgid / nig, fm = gid * WGM, gsz = (nM - fm) < WGM ? (nM - fm) : WGM;
;         u.pm = fm + ((wgid % nig) % gsz); u.pn = (wgid % nig) / gsz; return true;
;     }
;     pg8::Gemm g{A, Bt, lda, ldb, M, N, K}; pg8::StaticOrder S; S.init(M, N, C.G, (((C.bid & 31) * 8 + (C.bid >> 5)) + crot) % C.G);
;     pg8::gemm_phase<pg8::Epi<MODE>, pg8::StaticOrder, true, true>(C.lds, g, S, E);
	s_addc_u32 s9, s11, 0
	s_movk_i32 s27, 0x84
	v_writelane_b32 v253, s11, 13
	v_writelane_b32 v253, s8, 14
	s_nop 1
	v_writelane_b32 v253, s9, 15
	s_add_u32 s8, s12, 0x10080
	v_writelane_b32 v253, s12, 16
	s_addc_u32 s9, s13, 0
	s_add_i32 s10, s0, s3
	s_ashr_i32 s11, s10, 31
	v_writelane_b32 v253, s13, 17
	s_lshr_b32 s0, s11, 28
	v_writelane_b32 v253, s8, 18
	s_add_i32 s0, s10, s0
	s_nop 0
	v_writelane_b32 v253, s9, 19
	s_and_b32 s8, s0, 0xfff0
	s_sub_i32 s8, s10, s8
	s_bfe_i32 s9, s8, 0x80000
	s_bfe_u32 s9, s9, 0x3000c
	s_add_i32 s9, s8, s9
	s_and_b32 s12, s9, 0xf8
	s_sub_i32 s8, s8, s12
	s_ashr_i32 s0, s0, 4
	s_lshl_b32 s0, s0, 3
	s_sext_i32_i8 s8, s8
	s_add_i32 s12, s0, s8
	s_bfe_i32 s0, s9, 0x80000
	s_sext_i32_i16 s0, s0
	s_ashr_i32 s8, s0, 3
	s_lshr_b32 s0, s0, 3
	v_writelane_b32 v253, s8, 20
	s_bfe_i64 s[8:9], s[0:1], 0x100000
	s_lshl_b64 s[8:9], s[8:9], 17
	s_add_u32 s14, s45, s8
	s_addc_u32 s15, s46, s9
	v_writelane_b32 v253, s45, 21
	s_add_u32 s8, s14, 0x10000
	v_writelane_b32 v253, s46, 22
	s_addc_u32 s9, s15, 0
	v_writelane_b32 v253, s8, 23
	s_mul_hi_i32 s0, s12, 0x120000
	s_nop 0
	v_writelane_b32 v253, s9, 24
	s_mul_i32 s8, s12, 0x120000
	s_add_u32 s8, s31, s8
	v_writelane_b32 v253, s12, 25
	s_addc_u32 s9, s44, s0
	s_add_u32 s12, s8, 0x90000
	v_writelane_b32 v253, s8, 26
	s_addc_u32 s13, s9, 0
	s_nop 0
	v_writelane_b32 v253, s9, 27
	v_writelane_b32 v253, s12, 28
	s_add_u32 s8, s14, 0x10080
	s_nop 0
	v_writelane_b32 v253, s13, 29
	v_writelane_b32 v253, s14, 30
	s_addc_u32 s9, s15, 0
	s_lshr_b32 s0, s11, 22
	v_writelane_b32 v253, s15, 31
	v_writelane_b32 v253, s8, 32
	s_add_i32 s0, s10, s0
	s_nop 0
	v_writelane_b32 v253, s9, 33
	s_and_b32 s8, s0, 0xfffffc00
	s_ashr_i32 s0, s0, 10
	s_lshl_b32 s11, s0, 3
	s_sub_i32 s0, 2, s11
	s_min_u32 s12, s0, 8
	s_sub_i32 s10, s10, s8
	v_cvt_f32_ubyte0_e32 v1, s12
	v_cvt_f32_i32_e32 v0, s10
	v_rcp_iflag_f32_e32 v2, v1
	s_ashr_i32 s0, s10, 30
	s_or_b32 s0, s0, 1
	v_mul_f32_e32 v2, v0, v2
	v_trunc_f32_e32 v2, v2
	v_fma_f32 v0, -v2, v1, v0
	v_cmp_ge_f32_e64 s[8:9], |v0|, v1
	v_cvt_i32_f32_e32 v0, v2
	s_and_b64 s[8:9], s[8:9], exec
	s_cselect_b32 s0, s0, 0
	v_mov_b32_e32 v1, 0
	v_readfirstlane_b32 s8, v0
	s_add_i32 s0, s8, s0
	s_mul_i32 s8, s0, s12
	s_sub_i32 s10, s10, s8
	s_bfe_i64 s[8:9], s[0:1], 0x100000
	s_mul_hi_i32 s12, s8, 0x120000
	s_mul_i32 s13, s8, 0x120000
	s_sext_i32_i16 s8, s10
	s_add_i32 s10, s11, s8
	s_mov_b32 s8, s10
	s_ashr_i32 s11, s10, 31
	v_writelane_b32 v253, s8, 34
	s_sext_i32_i16 s0, s0
	v_mbcnt_lo_u32_b32 v0, -1, 0
	v_writelane_b32 v253, s9, 35
	s_lshl_b64 s[8:9], s[10:11], 17
	s_add_u32 s10, s31, s13
	s_addc_u32 s11, s44, s12
	v_writelane_b32 v253, s31, 36
	s_add_u32 s12, s10, 0x90000
	v_writelane_b32 v253, s44, 37
	s_addc_u32 s13, s11, 0
	v_writelane_b32 v253, s12, 38
	s_add_u32 s8, s47, s8
	s_addc_u32 s9, s48, s9
	v_writelane_b32 v253, s13, 39
	v_writelane_b32 v253, s47, 40
	v_writelane_b32 v253, s48, 41
	s_add_u32 s12, s8, 0x10000
	v_writelane_b32 v253, s8, 42
	s_addc_u32 s13, s9, 0
	v_mbcnt_hi_u32_b32 v178, -1, v0
	v_writelane_b32 v253, s9, 43
	v_writelane_b32 v253, s12, 44
	s_add_u32 s8, s10, 0x90080
	v_mov_b32_e32 v194, v1
	v_writelane_b32 v253, s13, 45
	v_writelane_b32 v253, s10, 46
	s_addc_u32 s9, s11, 0
	s_cmpk_lt_i32 s61, 0x200
	v_writelane_b32 v253, s11, 47
	v_writelane_b32 v253, s8, 48
	v_mov_b32_e32 v195, v1
	v_mov_b32_e32 v196, v1
	v_writelane_b32 v253, s9, 49
	s_cselect_b64 s[8:9], -1, 0
	v_writelane_b32 v253, s8, 50
	s_add_i32 s2, s2, s3
	v_mov_b32_e32 v197, v1
	v_writelane_b32 v253, s9, 51
	s_ashr_i32 s8, s2, 31
	s_lshr_b32 s8, s8, 27
	s_add_i32 s8, s2, s8
	s_and_b32 s9, s8, 0xffe0
	s_sub_i32 s2, s2, s9
	s_bfe_i32 s9, s2, 0x80000
	s_bfe_u32 s9, s9, 0x3000c
	s_add_i32 s9, s2, s9
	s_and_b32 s10, s9, 0xf8
	s_sub_i32 s2, s2, s10
	s_ashr_i32 s8, s8, 5
	s_bfe_i32 s9, s9, 0x80000
	s_lshl_b32 s8, s8, 3
	s_sext_i32_i16 s9, s9
	s_sext_i32_i8 s2, s2
	s_add_i32 s12, s8, s2
	s_lshr_b32 s2, s9, 3
	s_ashr_i32 s13, s12, 31
	s_ashr_i32 s59, s9, 3
	s_bfe_i64 s[8:9], s[2:3], 0x100000
	s_lshl_b64 s[10:11], s[12:13], 19
	s_lshl_b64 s[14:15], s[8:9], 19
	s_add_u32 s34, s22, s10
	s_addc_u32 s35, s23, s11
	s_add_u32 s42, s34, 0x40000
	v_writelane_b32 v253, s34, 52
	s_addc_u32 s43, s35, 0
;     __host__ __device__ bool next(int i, Unit& u) const {
;         const long L = (long)i * G + c; if (L >= nwg) return false;
;         int wgid = (int)L; { const int q = nwg / NXCD, r = nwg % NXCD, xcd = wgid % NXCD, off = wgid / NXCD; wgid = (xcd < r ? xcd * (q + 1) : r * (q + 1) + (xcd - r) * q) + off; }
;         const int nig = WGM * nN, gid = wgid / nig, fm = gid * WGM, gsz = (nM - fm) < WGM ? (nM - fm) : WGM;
;         u.pm = fm + ((wgid % nig) % gsz); u.pn = (wgid % nig) / gsz; return true;
;     }
;     pg8::Gemm g{A, Bt, lda, ldb, M, N, K}; pg8::StaticOrder S; S.init(M, N, C.G, (((C.bid & 31) * 8 + (C.bid >> 5)) + crot) % C.G);
;     pg8::gemm_phase<pg8::Epi<MODE>, pg8::StaticOrder, true, true>(C.lds, g, S, E);
	s_nop 0
	v_writelane_b32 v253, s35, 53
	v_writelane_b32 v253, s42, 54
	s_add_u32 s34, s40, s14
	s_nop 0
	v_writelane_b32 v253, s43, 55
	v_writelane_b32 v253, s40, 56
	s_nop 1
	v_writelane_b32 v253, s41, 57
	v_writelane_b32 v253, s14, 58
	s_addc_u32 s35, s41, s15
	s_nop 0
	v_writelane_b32 v253, s15, 59
	s_add_u32 s14, s34, 0x40000
	s_addc_u32 s15, s35, 0
	s_add_u32 s10, s28, s10
	v_writelane_b32 v253, s14, 60
	s_addc_u32 s11, s29, s11
	s_nop 0
	v_writelane_b32 v253, s15, 61
	s_add_u32 s14, s10, 0x40000
	v_writelane_b32 v253, s10, 62
	s_addc_u32 s15, s11, 0
	v_writelane_b32 v254, s14, 0
	v_writelane_b32 v253, s11, 63
	s_add_u32 s10, s34, 0x40080
	v_writelane_b32 v254, s15, 1
	v_writelane_b32 v254, s34, 2
	s_addc_u32 s11, s35, 0
	s_cmpk_lt_i32 s61, 0x800
	v_writelane_b32 v254, s35, 3
	v_writelane_b32 v254, s10, 4
	s_nop 1
	v_writelane_b32 v254, s11, 5
	s_cselect_b64 s[10:11], -1, 0
	s_add_i32 s1, s1, s3
	s_ashr_i32 s2, s1, 31
	s_lshr_b32 s2, s2, 25
	s_add_i32 s2, s1, s2
	s_and_b32 s3, s2, 0xff80
	s_sub_i32 s1, s1, s3
	s_bfe_i32 s3, s1, 0x80000
	s_bfe_u32 s3, s3, 0x3000c
	v_writelane_b32 v254, s10, 6
	s_add_i32 s3, s1, s3
	s_ashr_i32 s2, s2, 7
	v_writelane_b32 v254, s11, 7
	s_and_b32 s10, s3, 0xf8
	s_sub_i32 s1, s1, s10
	s_bfe_i32 s3, s3, 0x80000
	s_lshl_b32 s2, s2, 3
	s_sext_i32_i16 s3, s3
	s_sext_i32_i8 s1, s1
	s_add_i32 s14, s2, s1
	s_ashr_i32 s1, s3, 3
	v_writelane_b32 v254, s1, 8
	s_lshr_b32 s2, s3, 3
	s_mov_b32 s10, s14
	s_ashr_i32 s15, s14, 31
	s_bfe_i64 s[2:3], s[2:3], 0x100000
	v_writelane_b32 v254, s10, 9
	s_lshl_b64 s[2:3], s[2:3], 19
	s_mul_i32 s1, s97, s96
	v_writelane_b32 v254, s11, 10
	s_lshl_b64 s[10:11], s[14:15], 19
	s_add_u32 s2, s38, s2
	v_writelane_b32 v254, s38, 11
	s_addc_u32 s3, s39, s3
	s_add_u32 s14, s2, 0x40000
	v_writelane_b32 v254, s39, 12
	s_addc_u32 s15, s3, 0
	v_writelane_b32 v254, s14, 13
	s_add_u32 s10, s22, s10
	s_addc_u32 s11, s23, s11
	v_writelane_b32 v254, s15, 14
	s_add_u32 s14, s10, 0x40000
	v_writelane_b32 v254, s10, 15
	s_addc_u32 s15, s11, 0
	s_mul_i32 s1, s1, s26
	v_writelane_b32 v254, s11, 16
	v_writelane_b32 v254, s14, 17
	s_add_u32 s10, s2, 0x40080
	s_movk_i32 s26, 0x80
	v_writelane_b32 v254, s15, 18
	v_writelane_b32 v254, s2, 19
	s_addc_u32 s11, s3, 0
	s_mov_b32 s97, 0xf149f2ca
	v_writelane_b32 v254, s3, 20
	v_writelane_b32 v254, s10, 21
	s_lshl_b64 s[2:3], s[8:9], 21
	s_mov_b32 s8, s12
	v_writelane_b32 v254, s11, 22
	v_writelane_b32 v254, s8, 23
	s_nop 1
	v_writelane_b32 v254, s9, 24
	s_lshl_b64 s[8:9], s[12:13], 21
	s_add_u32 s2, s36, s2
	v_writelane_b32 v254, s36, 25
	s_addc_u32 s3, s37, s3
	s_add_u32 s10, s2, 0x100000
	v_writelane_b32 v254, s37, 26
	s_addc_u32 s11, s3, 0
	v_writelane_b32 v254, s10, 27
	s_add_u32 s8, s24, s8
	s_addc_u32 s9, s25, s9
	v_writelane_b32 v254, s11, 28
	v_writelane_b32 v254, s1, 29
	v_writelane_b32 v254, s0, 30
	s_mul_i32 s0, s4, 17
	v_writelane_b32 v254, s0, 31
	s_add_u32 s0, s8, 0x100000
	v_writelane_b32 v254, s8, 32
	s_addc_u32 s1, s9, 0
	s_mov_b32 s10, s89
	v_writelane_b32 v254, s9, 33
	v_writelane_b32 v254, s0, 34
	s_nop 1
	v_writelane_b32 v254, s1, 35
	s_add_u32 s0, s2, 0x100080
	v_writelane_b32 v254, s2, 36
	s_addc_u32 s1, s3, 0
	s_nop 0
	v_writelane_b32 v254, s3, 37
	v_writelane_b32 v254, s0, 38
	s_mov_b64 s[2:3], 0x80
	s_nop 0
	v_writelane_b32 v254, s1, 39
	s_add_u32 s0, s18, 0xc50000
	s_addc_u32 s1, s19, 0
	v_writelane_b32 v254, s0, 40
	s_ashr_i32 s31, s30, 31
	s_lshl_b32 s81, s96, 12
	v_writelane_b32 v254, s1, 41
	s_lshl_b32 s0, s20, 12
	v_writelane_b32 v254, s0, 42
	s_lshl_b32 s0, s20, 5
	v_writelane_b32 v254, s0, 43
	s_lshl_b32 s0, s96, 5
	v_writelane_b32 v254, s0, 44
	s_add_i32 s0, 0, 0x20040
	v_writelane_b32 v254, s0, 45
	s_add_i32 s0, 0, 0x20044
	v_writelane_b32 v254, s0, 46
	s_add_i32 s0, 0, 0x1b800
	v_writelane_b32 v254, s0, 47
	s_add_i32 s0, 0, 0x1b000
	v_writelane_b32 v254, s0, 48
	s_add_i32 s0, 0, 0x2400
	v_writelane_b32 v254, s0, 49
	s_mov_b32 s0, s30
	v_writelane_b32 v254, s0, 50
	s_lshl_b64 s[62:63], s[30:31], 4
	s_mov_b64 s[14:15], s[62:63]
	v_writelane_b32 v254, s1, 51
	s_mov_b32 s0, s58
	v_writelane_b32 v254, s0, 52
	s_nop 1
	v_writelane_b32 v254, s1, 53
	v_writelane_b32 v254, s59, 54
	v_writelane_b32 v254, s81, 55
	s_branch .LBB0_26

; __device__ __forceinline__ unsigned pkhw(float lo, float hi) { f32x2q v = {lo, hi}; bf16x2q b = __builtin_convertvector(v, bf16x2q); return __builtin_bit_cast(unsigned, b); }
; __device__ __forceinline__ void mla_unit(const Ctx& C, const Params& p, int unit) {
;     ...
;     bf16* Y = (bf16*)(p.ws + WS_Y) + (size_t)2 * T * 512;
; #pragma unroll
;     for (int g = 0; g < 2; ++g) {
;         float lt = lsum[g]; lt += __shfl_xor(lt, 16); lt += __shfl_xor(lt, 32);
;         const float inv = 1.0f / lt;
;         bf16* yp = Y + (tok0 + q0w + 16 * g + fr) * 512 + h * 64 + fq * 4;
; #pragma unroll
;         for (int d = 0; d < 4; ++d) { v2u w; w.x = pkhw(o[g][d][0] * inv, o[g][d][1] * inv); w.y = pkhw(o[g][d][2] * inv, o[g][d][3] * inv); *(v2u*)(yp + d * 16) = w; }
;     }
.LBB0_486:
	s_add_i32 s9, s9, s96
	v_mov_b32_e32 v130, v190
	v_mov_b32_e32 v131, v190
	v_readlane_b32 s0, v252, 37
	v_readlane_b32 s1, v252, 38
	v_permlane32_swap_b32_e32 v130, v131
	v_add_f32_e32 v0, v130, v131
	v_div_scale_f32 v6, s[10:11], v0, v0, 1.0
	v_rcp_f32_e32 v7, v6
	v_div_scale_f32 v8, vcc, 1.0, v0, 1.0
	v_and_b32_e32 v130, 1, v193
	v_fma_f32 v9, -v6, v7, 1.0
	v_fmac_f32_e32 v7, v9, v7
	v_mul_f32_e32 v9, v8, v7
	v_fma_f32 v11, -v6, v9, v8
	v_fmac_f32_e32 v9, v11, v7
	v_lshl_or_b32 v130, v130, 4, v118
	v_fma_f32 v6, -v6, v9, v8
	v_div_fmas_f32 v6, v6, v7, v9
	v_div_fixup_f32 v0, v6, v0, 1.0
	v_lshrrev_b32_e32 v131, 1, v193
	v_lshlrev_b32_e32 v2, 1, v120
	v_lshl_add_u32 v2, v131, 3, v2
	v_mov_b32_e32 v3, 0
	v_lshl_add_u64 v[2:3], s[0:1], 0, v[2:3]
	s_movk_i32 s93, 0x400
	v_mad_u64_u32 v[2:3], s[10:11], v130, s93, v[2:3]
	v_pk_mul_f32 v[4:5], v[64:65], v[0:1] op_sel_hi:[1,0]
	v_pk_mul_f32 v[6:7], v[66:67], v[0:1] op_sel_hi:[1,0]
	v_cvt_pk_bf16_f32 v8, v4, v5
	v_cvt_pk_bf16_f32 v9, v6, v7
	global_store_dwordx2 v[2:3], v[8:9], off
	v_pk_mul_f32 v[4:5], v[68:69], v[0:1] op_sel_hi:[1,0]
	v_pk_mul_f32 v[6:7], v[70:71], v[0:1] op_sel_hi:[1,0]
	v_cvt_pk_bf16_f32 v10, v4, v5
	v_cvt_pk_bf16_f32 v11, v6, v7
	global_store_dwordx2 v[2:3], v[10:11], off offset:16
	v_pk_mul_f32 v[4:5], v[72:73], v[0:1] op_sel_hi:[1,0]
	v_pk_mul_f32 v[6:7], v[74:75], v[0:1] op_sel_hi:[1,0]
	v_cvt_pk_bf16_f32 v8, v4, v5
	v_cvt_pk_bf16_f32 v9, v6, v7
	global_store_dwordx2 v[2:3], v[8:9], off offset:32
	v_pk_mul_f32 v[4:5], v[76:77], v[0:1] op_sel_hi:[1,0]
	v_pk_mul_f32 v[6:7], v[78:79], v[0:1] op_sel_hi:[1,0]
	v_cvt_pk_bf16_f32 v10, v4, v5
	v_cvt_pk_bf16_f32 v11, v6, v7
	global_store_dwordx2 v[2:3], v[10:11], off offset:48
	v_pk_mul_f32 v[4:5], v[48:49], v[0:1] op_sel_hi:[1,0]
	v_pk_mul_f32 v[6:7], v[50:51], v[0:1] op_sel_hi:[1,0]
	v_cvt_pk_bf16_f32 v8, v4, v5
	v_cvt_pk_bf16_f32 v9, v6, v7
	global_store_dwordx2 v[2:3], v[8:9], off offset:64
	v_pk_mul_f32 v[4:5], v[52:53], v[0:1] op_sel_hi:[1,0]
	v_pk_mul_f32 v[6:7], v[54:55], v[0:1] op_sel_hi:[1,0]
	v_cvt_pk_bf16_f32 v10, v4, v5
	v_cvt_pk_bf16_f32 v11, v6, v7
	global_store_dwordx2 v[2:3], v[10:11], off offset:80
	v_pk_mul_f32 v[4:5], v[56:57], v[0:1] op_sel_hi:[1,0]
	v_pk_mul_f32 v[6:7], v[58:59], v[0:1] op_sel_hi:[1,0]
	v_cvt_pk_bf16_f32 v8, v4, v5
	v_cvt_pk_bf16_f32 v9, v6, v7
	global_store_dwordx2 v[2:3], v[8:9], off offset:96
	v_pk_mul_f32 v[4:5], v[60:61], v[0:1] op_sel_hi:[1,0]
	v_pk_mul_f32 v[6:7], v[62:63], v[0:1] op_sel_hi:[1,0]
	v_cvt_pk_bf16_f32 v10, v4, v5
	v_cvt_pk_bf16_f32 v11, v6, v7
	global_store_dwordx2 v[2:3], v[10:11], off offset:112
	s_cmpk_gt_i32 s9, 0x3ff
	s_cbranch_scc1 .LBB0_535

; #define LAS __attribute__((address_space(3)))
; __device__ __forceinline__ void mla_unit(const Ctx& C, const Params& p, int unit) {
;     ...
;     bf16x8 qf[2][3];
; #pragma unroll
;     for (int g = 0; g < 2; ++g) {
;         const size_t qrow = tok0 + q0w + 16 * g + fr;
;         const bf16* qp = QM + qrow * 768 + h * 96 + fq * 8;
;         qf[g][0] = *(const bf16x8*)qp; qf[g][1] = *(const bf16x8*)(qp + 32);
;         const v4u raw = *(const v4u*)(qp + 64);
;         const f32x2* cs = (const f32x2*)(p.ws + WS_ROPE) + qrow * 16 + (fq & 1) * 8;
;         const float own[8] = {bflo(raw.x), bfhi(raw.x), bflo(raw.y), bfhi(raw.y), bflo(raw.z), bfhi(raw.z), bflo(raw.w), bfhi(raw.w)};
;         float res[8];
; #pragma unroll
;         for (int e = 0; e < 8; ++e) { const float oth = __shfl_xor(own[e], 32); const f32x2 c = cs[e]; res[e] = (fq < 2) ? (own[e] * c.x - oth * c.y) : (own[e] * c.x + oth * c.y); }
;         v4u rw; rw.x = pkhw(res[0], res[1]); rw.y = pkhw(res[2], res[3]); rw.z = pkhw(res[4], res[5]); rw.w = pkhw(res[6], res[7]);
;         qf[g][2] = __builtin_bit_cast(bf16x8, rw);
;     }
;     float m[2] = {-1e30f, -1e30f}, lsum[2] = {0.f, 0.f};
;     f32x4 o[2][4];
; #pragma unroll
;     for (int g = 0; g < 2; ++g)
; #pragma unroll
;         for (int d = 0; d < 4; ++d) o[g][d] = (f32x4){0.f, 0.f, 0.f, 0.f};
;     const int nt = 4 * (qb + 1), my_last = (q0w + 31) >> 6;
;     const int kc0 = tid, kc1 = tid + 512;
;     const int key0 = kc0 / 12, part0 = kc0 % 12, key1 = kc1 / 12, part1 = kc1 % 12; const bool has1 = kc1 < 768;
;     const bf16* ksrc0 = (part0 < 8) ? (KM + (tok0 + key0) * 512 + h * 64 + part0 * 8) : (P + (tok0 + key0) * PN + C_KPE + (part0 - 8) * 8);
;     const bf16* ksrc1 = (part1 < 8) ? (KM + (tok0 + key1) * 512 + h * 64 + part1 * 8) : (P + (tok0 + key1) * PN + C_KPE + (part1 - 8) * 8);
;     const size_t kstep0 = (part0 < 8) ? (size_t)64 * 512 : (size_t)64 * PN, kstep1 = (part1 < 8) ? (size_t)64 * 512 : (size_t)64 * PN;
;     const int kdst0 = key0 * AK_ROW + part0 * 16, kdst1 = key1 * AK_ROW + part1 * 16;
;     const bf16* vsrc = VTM + (size_t)(h * 64 + (tid >> 3)) * T + tok0 + (tid & 7) * 8;
;     const int vdst = AK_BYTES + (tid >> 3) * AV_ROW + ((((tid & 7) >> 2) * 32 + (2 * (tid & 1)) * 8 + (((tid & 7) >> 1) & 1) * 4) * 2);
;     LAS unsigned char* lds = C.lds;
;     v4u r0[2], r1[2], r2[2];
; #pragma unroll
.LBB0_499:
	s_or_b64 exec, exec, s[20:21]
	s_movk_i32 s10, 0xd0
	v_mul_lo_u32 v0, v40, s10
	s_movk_i32 s10, 0x90
	v_lshlrev_b32_e32 v40, 5, v50
	v_lshl_add_u32 v3, v53, 4, v0
	v_mul_lo_u32 v0, v41, s10
	v_and_b32_e32 v2, 64, v42
	v_and_b32_e32 v40, 32, v40
	v_and_b32_e32 v41, 8, v51
	v_or3_b32 v2, v41, v40, v2
	global_load_dwordx4 v[40:43], v[128:129], off offset:128
	v_and_b32_e32 v238, 1, v193
	v_lshl_or_b32 v246, v238, 4, v118
	v_lshrrev_b32_e32 v239, 1, v193
	v_mul_u32_u24_e32 v240, 3, v120
	v_lshl_add_u32 v240, v239, 4, v240
	v_mov_b32_e32 v241, 0
	v_lshl_add_u64 v[240:241], s[28:29], 0, v[240:241]
	s_movk_i32 s93, 0x600
	v_mad_u64_u32 v[240:241], s[98:99], v246, s93, v[240:241]
	global_load_dwordx4 v[198:201], v[240:241], off
	global_load_dwordx4 v[202:205], v[240:241], off offset:32
	global_load_dwordx4 v[206:209], v[240:241], off offset:64
	global_load_dwordx4 v[210:213], v[240:241], off offset:96
	global_load_dwordx4 v[214:217], v[240:241], off offset:128
	global_load_dwordx4 v[218:221], v[240:241], off offset:160
	v_readlane_b32 s94, v251, 29
	v_readlane_b32 s95, v251, 30
	v_lshlrev_b32_e32 v242, 6, v239
	v_mov_b32_e32 v243, 0
	v_lshl_add_u64 v[242:243], s[94:95], 0, v[242:243]
	s_movk_i32 s93, 0x80
	v_mad_u64_u32 v[242:243], s[98:99], v246, s93, v[242:243]
	global_load_dwordx4 v[222:225], v[242:243], off
	global_load_dwordx4 v[226:229], v[242:243], off offset:16
	global_load_dwordx4 v[230:233], v[242:243], off offset:32
	global_load_dwordx4 v[234:237], v[242:243], off offset:48
	v_add_u32_e32 v53, 0, v3
	v_add_u32_e32 v187, v0, v2
	v_lshrrev_b32_e32 v238, 3, v185
	v_mul_u32_u24_e32 v238, 0x90, v238
	v_bfe_u32 v239, v185, 1, 2
	v_lshl_add_u32 v238, v239, 5, v238
	v_and_b32_e32 v239, 1, v185
	v_lshl_add_u32 v187, v239, 3, v238
	s_waitcnt vmcnt(13)
	ds_write_b128 v53, v[20:23]
	s_and_saveexec_b64 s[10:11], s[0:1]
	s_xor_b64 s[0:1], exec, s[10:11]
	s_cbranch_execz .LBB0_501
	v_add_u32_e32 v0, 0, v187
	v_add_u32_e32 v0, 0x3000, v0
	s_waitcnt vmcnt(12)
	ds_write2_b64 v0, v[32:33], v[34:35] offset0:128 offset1:130
.LBB0_501:
	s_or_saveexec_b64 s[0:1], s[0:1]
	s_movk_i32 s10, 0xd0
	v_mul_lo_u32 v0, v48, s10
	s_waitcnt vmcnt(11)
	v_mov_b64_e32 v[50:51], v[38:39]
	v_lshl_add_u32 v189, v52, 4, v0
	v_mov_b32_e32 v0, v3
	v_mov_b64_e32 v[48:49], v[36:37]
	s_xor_b64 exec, exec, s[0:1]
	s_cbranch_execz .LBB0_503
	v_add_u32_e32 v0, 0, v189
	ds_write_b128 v0, v[24:27]
	v_add_u32_e32 v0, 0, v187
	v_add_u32_e32 v0, 0x3000, v0
	v_mov_b64_e32 v[50:51], v[30:31]
	ds_write2_b64 v0, v[32:33], v[34:35] offset0:128 offset1:130
	ds_write_b128 v53, v[36:39] offset:22528
	v_mov_b32_e32 v0, v189
	v_mov_b64_e32 v[48:49], v[28:29]
; __device__ __forceinline__ unsigned pkhw(float lo, float hi) { f32x2q v = {lo, hi}; bf16x2q b = __builtin_convertvector(v, bf16x2q); return __builtin_bit_cast(unsigned, b); }
; __device__ __forceinline__ void mla_unit(const Ctx& C, const Params& p, int unit) {
;     ...
;     for (int g = 0; g < 2; ++g) {
;         const size_t qrow = tok0 + q0w + 16 * g + fr;
;         const bf16* qp = QM + qrow * 768 + h * 96 + fq * 8;
;         qf[g][0] = *(const bf16x8*)qp; qf[g][1] = *(const bf16x8*)(qp + 32);
;         const v4u raw = *(const v4u*)(qp + 64);
;         const f32x2* cs = (const f32x2*)(p.ws + WS_ROPE) + qrow * 16 + (fq & 1) * 8;
;         const float own[8] = {bflo(raw.x), bfhi(raw.x), bflo(raw.y), bfhi(raw.y), bflo(raw.z), bfhi(raw.z), bflo(raw.w), bfhi(raw.w)};
;         float res[8];
; #pragma unroll
;         for (int e = 0; e < 8; ++e) { const float oth = __shfl_xor(own[e], 32); const f32x2 c = cs[e]; res[e] = (fq < 2) ? (own[e] * c.x - oth * c.y) : (own[e] * c.x + oth * c.y); }
;         v4u rw; rw.x = pkhw(res[0], res[1]); rw.y = pkhw(res[2], res[3]); rw.z = pkhw(res[4], res[5]); rw.w = pkhw(res[6], res[7]);
;         qf[g][2] = __builtin_bit_cast(bf16x8, rw);
;     }
;     float m[2] = {-1e30f, -1e30f}, lsum[2] = {0.f, 0.f};
;     f32x4 o[2][4];
; #pragma unroll
;     for (int g = 0; g < 2; ++g)
; #pragma unroll
;         for (int d = 0; d < 4; ++d) o[g][d] = (f32x4){0.f, 0.f, 0.f, 0.f};
;     const int nt = 4 * (qb + 1), my_last = (q0w + 31) >> 6;
;     const int kc0 = tid, kc1 = tid + 512;
;     const int key0 = kc0 / 12, part0 = kc0 % 12, key1 = kc1 / 12, part1 = kc1 % 12; const bool has1 = kc1 < 768;
;     const bf16* ksrc0 = (part0 < 8) ? (KM + (tok0 + key0) * 512 + h * 64 + part0 * 8) : (P + (tok0 + key0) * PN + C_KPE + (part0 - 8) * 8);
;     const bf16* ksrc1 = (part1 < 8) ? (KM + (tok0 + key1) * 512 + h * 64 + part1 * 8) : (P + (tok0 + key1) * PN + C_KPE + (part1 - 8) * 8);
;     const size_t kstep0 = (part0 < 8) ? (size_t)64 * 512 : (size_t)64 * PN, kstep1 = (part1 < 8) ? (size_t)64 * 512 : (size_t)64 * PN;
;     const int kdst0 = key0 * AK_ROW + part0 * 16, kdst1 = key1 * AK_ROW + part1 * 16;
;     const bf16* vsrc = VTM + (size_t)(h * 64 + (tid >> 3)) * T + tok0 + (tid & 7) * 8;
;     const int vdst = AK_BYTES + (tid >> 3) * AV_ROW + ((((tid & 7) >> 2) * 32 + (2 * (tid & 1)) * 8 + (((tid & 7) >> 1) & 1) * 4) * 2);
.LBB0_503:
	s_or_b64 exec, exec, s[0:1]
	v_add_u32_e32 v0, 0, v0
	ds_write_b128 v0, v[48:51] offset:22528
	v_add_u32_e32 v0, 0, v187
	v_add_u32_e32 v0, 0x8800, v0
	s_mov_b64 s[0:1], -1
	s_cmp_lg_u32 s31, 16
	v_lshlrev_b32_e32 v188, 2, v193
	s_waitcnt vmcnt(0)
	ds_write2_b64 v0, v[40:41], v[42:43] offset0:128 offset1:130
	s_waitcnt lgkmcnt(0)
	s_barrier
	s_cbranch_scc0 .LBB0_533
	v_mov_b32_e32 v49, v106
	v_mov_b32_e32 v106, v105
	v_pk_mul_f32 v[50:51], v[106:107], v[172:173]
	v_cmp_gt_u32_e32 vcc, 2, v193
	v_mov_b32_e32 v48, v104
	s_lshl_b32 s0, s31, 2
	v_cndmask_b32_e64 v51, v51, -v51, vcc
	v_cndmask_b32_e64 v50, v50, -v50, vcc
	v_pk_fma_f32 v[48:49], v[48:49], v[170:171], v[50:51]
	v_mov_b32_e32 v51, v102
	v_mov_b32_e32 v102, v101
	v_pk_mul_f32 v[52:53], v[102:103], v[168:169]
	v_mov_b32_e32 v50, v100
	v_cndmask_b32_e64 v53, v53, -v53, vcc
	v_cndmask_b32_e64 v52, v52, -v52, vcc
	v_pk_fma_f32 v[50:51], v[50:51], v[166:167], v[52:53]
	v_mov_b32_e32 v53, v98
	v_mov_b32_e32 v98, v97
	v_pk_mul_f32 v[54:55], v[98:99], v[164:165]
	v_mov_b32_e32 v52, v96
	v_cndmask_b32_e64 v55, v55, -v55, vcc
	v_cndmask_b32_e64 v54, v54, -v54, vcc
	v_pk_fma_f32 v[52:53], v[52:53], v[162:163], v[54:55]
	v_mov_b32_e32 v55, v46
	v_mov_b32_e32 v46, v45
	v_mov_b32_e32 v54, v44
	v_pk_mul_f32 v[44:45], v[46:47], v[160:161]
	v_cvt_pk_bf16_f32 v46, v52, v53
	v_cndmask_b32_e64 v45, v45, -v45, vcc
	v_cndmask_b32_e64 v44, v44, -v44, vcc
	v_pk_fma_f32 v[54:55], v[54:55], v[158:159], v[44:45]
	v_cvt_pk_bf16_f32 v44, v48, v49
	v_mov_b32_e32 v49, v94
	v_mov_b32_e32 v94, v93
	v_cvt_pk_bf16_f32 v45, v50, v51
	v_pk_mul_f32 v[50:51], v[94:95], v[156:157]
	v_mov_b32_e32 v48, v92
	v_cndmask_b32_e64 v51, v51, -v51, vcc
	v_cndmask_b32_e64 v50, v50, -v50, vcc
	v_pk_fma_f32 v[48:49], v[48:49], v[154:155], v[50:51]
	v_mov_b32_e32 v51, v90
	v_mov_b32_e32 v90, v89
	v_pk_mul_f32 v[52:53], v[90:91], v[152:153]
	v_mov_b32_e32 v50, v88
	v_cndmask_b32_e64 v53, v53, -v53, vcc
	v_cndmask_b32_e64 v52, v52, -v52, vcc
	v_pk_fma_f32 v[50:51], v[50:51], v[150:151], v[52:53]
	v_mov_b32_e32 v53, v86
	v_mov_b32_e32 v86, v85
	v_cvt_pk_bf16_f32 v47, v54, v55
	v_pk_mul_f32 v[54:55], v[86:87], v[114:115]
	v_mov_b32_e32 v52, v84
	v_cndmask_b32_e64 v55, v55, -v55, vcc
	v_cndmask_b32_e64 v54, v54, -v54, vcc
	v_pk_fma_f32 v[52:53], v[52:53], v[112:113], v[54:55]
	v_mov_b32_e32 v55, v62
	v_mov_b32_e32 v62, v61
	s_sub_i32 s31, 64, s0
	s_and_b32 s0, s4, 0x3ffffffc
	v_pk_mul_f32 v[56:57], v[62:63], v[110:111]
	s_or_b32 s0, s35, s0
	v_mov_b32_e32 v54, v60
	v_cndmask_b32_e64 v57, v57, -v57, vcc
	v_cndmask_b32_e64 v56, v56, -v56, vcc
	s_lshl_b32 s0, s0, 2
	v_pk_fma_f32 v[54:55], v[54:55], v[108:109], v[56:57]
	s_sub_i32 s0, 64, s0
	v_mov_b32_e32 v76, v1
	v_mov_b32_e32 v77, v1
	v_mov_b32_e32 v78, v1
	v_mov_b32_e32 v79, v1
	v_cvt_pk_bf16_f32 v60, v48, v49
	v_cvt_pk_bf16_f32 v61, v50, v51
	v_cvt_pk_bf16_f32 v62, v52, v53
	v_cvt_pk_bf16_f32 v63, v54, v55
	s_addk_i32 s34, 0xf1f
	v_or_b32_e32 v151, s30, v192
	s_lshr_b32 s0, s0, 1
	v_mov_b64_e32 v[56:57], v[76:77]
	v_mov_b64_e32 v[48:49], v[76:77]
	v_mov_b64_e32 v[52:53], v[76:77]
	v_mov_b64_e32 v[82:83], v[78:79]
	v_mov_b64_e32 v[68:69], v[76:77]
	v_mov_b64_e32 v[64:65], v[76:77]
	v_mov_b64_e32 v[72:73], v[76:77]
	s_ashr_i32 s34, s34, 6
	v_lshlrev_b32_e32 v0, 2, v193
	s_max_u32 s35, s0, 1
	v_mul_u32_u24_e32 v153, 0xd0, v192
	v_or_b32_e32 v155, 16, v151
	v_add_u32_e32 v156, 14, v151
	v_add_u32_e32 v157, 13, v151
	v_mul_u32_u24_e32 v158, 0x90, v192
	v_lshl_add_u32 v159, v193, 4, 0
	s_mov_b32 s90, 0
	v_mov_b32_e32 v152, 0xf149f2ca
	v_mov_b32_e32 v190, 0
	v_mov_b64_e32 v[58:59], v[78:79]
	v_mov_b64_e32 v[50:51], v[78:79]
	v_mov_b64_e32 v[54:55], v[78:79]
	v_mov_b64_e32 v[80:81], v[76:77]
	v_mov_b64_e32 v[70:71], v[78:79]
	v_mov_b64_e32 v[66:67], v[78:79]
	v_mov_b64_e32 v[74:75], v[78:79]
	v_mov_b32_e32 v191, 0
	v_mov_b32_e32 v154, 0xf149f2ca
	v_mov_b32_e32 v4, v198
	v_mov_b32_e32 v5, v199
	v_mov_b32_e32 v6, v200
	v_mov_b32_e32 v7, v201
	v_mov_b32_e32 v8, v202
	v_mov_b32_e32 v9, v203
	v_mov_b32_e32 v10, v204
	v_mov_b32_e32 v11, v205
	v_mov_b32_e32 v12, v206
	v_mov_b32_e32 v13, v207
	v_mov_b32_e32 v14, v208
	v_mov_b32_e32 v15, v209
	v_mov_b32_e32 v16, v210
	v_mov_b32_e32 v17, v211
	v_mov_b32_e32 v18, v212
	v_mov_b32_e32 v19, v213
	v_lshlrev_b32_e32 v238, 16, v214
	v_and_b32_e32 v239, 0xffff0000, v214
	v_lshlrev_b32_e32 v240, 16, v218
	v_and_b32_e32 v241, 0xffff0000, v218
	v_mul_f32_e32 v242, v240, v223
	v_mul_f32_e32 v243, v241, v225
	v_mul_f32_e32 v244, v238, v223
	v_mul_f32_e32 v245, v239, v225
	v_fma_f32 v242, v238, v222, -v242
	v_fma_f32 v243, v239, v224, -v243
	v_fma_f32 v244, v240, v222, v244
	v_fma_f32 v245, v241, v224, v245
	v_cvt_pk_bf16_f32 v44, v242, v243
	v_cvt_pk_bf16_f32 v80, v244, v245
	v_lshlrev_b32_e32 v238, 16, v215
	v_and_b32_e32 v239, 0xffff0000, v215
	v_lshlrev_b32_e32 v240, 16, v219
	v_and_b32_e32 v241, 0xffff0000, v219
	v_mul_f32_e32 v242, v240, v227
	v_mul_f32_e32 v243, v241, v229
	v_mul_f32_e32 v244, v238, v227
	v_mul_f32_e32 v245, v239, v229
	v_fma_f32 v242, v238, v226, -v242
	v_fma_f32 v243, v239, v228, -v243
	v_fma_f32 v244, v240, v226, v244
	v_fma_f32 v245, v241, v228, v245
	v_cvt_pk_bf16_f32 v45, v242, v243
	v_cvt_pk_bf16_f32 v81, v244, v245
	v_lshlrev_b32_e32 v238, 16, v216
	v_and_b32_e32 v239, 0xffff0000, v216
	v_lshlrev_b32_e32 v240, 16, v220
	v_and_b32_e32 v241, 0xffff0000, v220
	v_mul_f32_e32 v242, v240, v231
	v_mul_f32_e32 v243, v241, v233
	v_mul_f32_e32 v244, v238, v231
	v_mul_f32_e32 v245, v239, v233
	v_fma_f32 v242, v238, v230, -v242
	v_fma_f32 v243, v239, v232, -v243
	v_fma_f32 v244, v240, v230, v244
	v_fma_f32 v245, v241, v232, v245
	v_cvt_pk_bf16_f32 v46, v242, v243
	v_cvt_pk_bf16_f32 v82, v244, v245
	v_lshlrev_b32_e32 v238, 16, v217
	v_and_b32_e32 v239, 0xffff0000, v217
	v_lshlrev_b32_e32 v240, 16, v221
	v_and_b32_e32 v241, 0xffff0000, v221
	v_mul_f32_e32 v242, v240, v235
	v_mul_f32_e32 v243, v241, v237
	v_mul_f32_e32 v244, v238, v235
	v_mul_f32_e32 v245, v239, v237
	v_fma_f32 v242, v238, v234, -v242
	v_fma_f32 v243, v239, v236, -v243
	v_fma_f32 v244, v240, v234, v244
	v_fma_f32 v245, v241, v236, v245
	v_cvt_pk_bf16_f32 v47, v242, v243
	v_cvt_pk_bf16_f32 v83, v244, v245
	v_mov_b32_e32 v60, 0
	v_mov_b32_e32 v61, 0
	v_mov_b32_e32 v62, 0
	v_mov_b32_e32 v63, 0
	v_and_b32_e32 v238, 1, v193
	v_lshl_or_b32 v248, v238, 4, v151
	v_lshl_or_b32 v238, v238, 4, v192
	v_lshrrev_b32_e32 v239, 1, v193
	v_mul_u32_u24_e32 v246, 0xd0, v238
	v_lshl_add_u32 v246, v239, 4, v246
	v_mul_u32_u24_e32 v247, 0x90, v238
	v_lshl_add_u32 v247, v239, 4, v247
	v_lshlrev_b32_e32 v249, 2, v239

; #define LAS __attribute__((address_space(3)))
; __device__ __forceinline__ void mla_unit(const Ctx& C, const Params& p, int unit) {
;     ...
;             const LAS unsigned char* Kb = lds + ((kp & 1) * 2 + sub) * ABUF; const LAS unsigned char* Vb = Kb + AK_BYTES;
;             const int k0 = kt * 64;
;             f32x4 s[2][4];
; #pragma unroll
;             for (int g = 0; g < 2; ++g)
; #pragma unroll
;                 for (int blk = 0; blk < 4; ++blk) s[g][blk] = (f32x4){0.f, 0.f, 0.f, 0.f};
; #pragma unroll
;             for (int kk = 0; kk < 3; ++kk)
; #pragma unroll
;                 for (int blk = 0; blk < 4; ++blk) {
;                     const bf16x8 kf = *(const LAS bf16x8*)(Kb + (blk * 16 + fr) * AK_ROW + (kk * 32 + fq * 8) * 2);
; #pragma unroll
;                     for (int g = 0; g < 2; ++g) s[g][blk] = __builtin_amdgcn_mfma_f32_16x16x32_bf16(kf, qf[g][kk], s[g][blk], 0, 0, 0);
;                 }
;             const bool need_mask = (k0 + 63 > q0w);
;             bf16x8 pf[2][2];
; #pragma unroll
;             for (int g = 0; g < 2; ++g) {
;                 const int qi = q0w + 16 * g + fr;
;                 if (need_mask) {
;                     asm volatile("" ::: "memory");
; #pragma unroll
;                     for (int blk = 0; blk < 4; ++blk)
; #pragma unroll
;                         for (int j = 0; j < 4; ++j) { const int key = k0 + blk * 16 + fq * 4 + j; if (key > qi) s[g][blk][j] = -1e30f; }
;                     asm volatile("" ::: "memory");
;                 }
.LBB0_514:
	s_or_b32 s1, s4, s88
	s_mulk_i32 s1, 0x5800
	v_add_u32_e32 v2, s1, v246
	v_add_u32_e32 v160, s1, v247
	ds_read_b128 v[198:201], v2
	ds_read_b128 v[202:205], v2 offset:6656
	ds_read_b128 v[206:209], v2 offset:32
	ds_read_b128 v[210:213], v2 offset:6688
	ds_read_b128 v[214:217], v2 offset:64
	ds_read_b128 v[218:221], v2 offset:6720
	ds_read_b128 v[222:225], v2 offset:96
	ds_read_b128 v[226:229], v2 offset:6752
	ds_read_b128 v[230:233], v2 offset:128
	ds_read_b128 v[234:237], v2 offset:6784
	ds_read_b128 v[238:241], v2 offset:160
	ds_read_b128 v[242:245], v2 offset:6816
	s_lshl_b32 s0, s0, 6
	s_or_b32 s1, s0, 63
	s_waitcnt lgkmcnt(10)
	v_mfma_f32_32x32x16_bf16 v[84:99], v[198:201], v[4:7], 0
	v_mfma_f32_32x32x16_bf16 v[100:115], v[202:205], v[4:7], 0
	s_waitcnt lgkmcnt(8)
	v_mfma_f32_32x32x16_bf16 v[84:99], v[206:209], v[8:11], v[84:99]
	v_mfma_f32_32x32x16_bf16 v[100:115], v[210:213], v[8:11], v[100:115]
	ds_read_b128 v[198:201], v160 offset:13312
	ds_read_b128 v[202:205], v160 offset:17920
	ds_read_b128 v[206:209], v160 offset:13344
	ds_read_b128 v[210:213], v160 offset:17952
	s_waitcnt lgkmcnt(10)
	v_mfma_f32_32x32x16_bf16 v[84:99], v[214:217], v[12:15], v[84:99]
	v_mfma_f32_32x32x16_bf16 v[100:115], v[218:221], v[12:15], v[100:115]
	s_waitcnt lgkmcnt(8)
	v_mfma_f32_32x32x16_bf16 v[84:99], v[222:225], v[16:19], v[84:99]
	v_mfma_f32_32x32x16_bf16 v[100:115], v[226:229], v[16:19], v[100:115]
	ds_read_b128 v[214:217], v160 offset:13376
	ds_read_b128 v[218:221], v160 offset:17984
	ds_read_b128 v[222:225], v160 offset:13408
	ds_read_b128 v[226:229], v160 offset:18016
	s_waitcnt lgkmcnt(10)
	v_mfma_f32_32x32x16_bf16 v[84:99], v[230:233], v[44:47], v[84:99]
	v_mfma_f32_32x32x16_bf16 v[100:115], v[234:237], v[44:47], v[100:115]
	s_waitcnt lgkmcnt(8)
	v_mfma_f32_32x32x16_bf16 v[84:99], v[238:241], v[80:83], v[84:99]
	v_mfma_f32_32x32x16_bf16 v[100:115], v[242:245], v[80:83], v[100:115]
	s_cmp_gt_i32 s1, s30
	s_nop 11
	s_cbranch_scc0 .Lmla_nomask
	v_or_b32_e32 v166, s0, v249
	v_sub_u32_e32 v130, v248, v166
	v_cmp_gt_i32_e64 s[38:39], 0, v130
	v_cmp_gt_i32_e64 s[40:41], 1, v130
	v_cmp_gt_i32_e64 s[42:43], 2, v130
	v_cmp_gt_i32_e64 s[44:45], 3, v130
	v_cmp_gt_i32_e64 s[46:47], 8, v130
	v_cmp_gt_i32_e64 s[48:49], 9, v130
	v_cmp_gt_i32_e64 s[50:51], 10, v130
	v_cmp_gt_i32_e64 s[52:53], 11, v130
	v_cndmask_b32_e64 v84, v84, v181, s[38:39]
	v_cndmask_b32_e64 v85, v85, v181, s[40:41]
	v_cndmask_b32_e64 v86, v86, v181, s[42:43]
	v_cndmask_b32_e64 v87, v87, v181, s[44:45]
	v_cndmask_b32_e64 v88, v88, v181, s[46:47]
	v_cndmask_b32_e64 v89, v89, v181, s[48:49]
	v_cndmask_b32_e64 v90, v90, v181, s[50:51]
	v_cndmask_b32_e64 v91, v91, v181, s[52:53]
	v_cmp_gt_i32_e64 s[38:39], 16, v130
	v_cmp_gt_i32_e64 s[40:41], 17, v130
	v_cmp_gt_i32_e64 s[42:43], 18, v130
	v_cmp_gt_i32_e64 s[44:45], 19, v130
	v_cmp_gt_i32_e64 s[46:47], 24, v130
	v_cmp_gt_i32_e64 s[48:49], 25, v130
	v_cmp_gt_i32_e64 s[50:51], 26, v130
	v_cmp_gt_i32_e64 s[52:53], 27, v130
	v_cndmask_b32_e64 v92, v92, v181, s[38:39]
	v_cndmask_b32_e64 v93, v93, v181, s[40:41]
	v_cndmask_b32_e64 v94, v94, v181, s[42:43]
	v_cndmask_b32_e64 v95, v95, v181, s[44:45]
	v_cndmask_b32_e64 v96, v96, v181, s[46:47]
	v_cndmask_b32_e64 v97, v97, v181, s[48:49]
	v_cndmask_b32_e64 v98, v98, v181, s[50:51]
	v_cndmask_b32_e64 v99, v99, v181, s[52:53]
	v_cmp_gt_i32_e64 s[38:39], 32, v130
	v_cmp_gt_i32_e64 s[40:41], 33, v130
	v_cmp_gt_i32_e64 s[42:43], 34, v130
	v_cmp_gt_i32_e64 s[44:45], 35, v130
	v_cmp_gt_i32_e64 s[46:47], 40, v130
	v_cmp_gt_i32_e64 s[48:49], 41, v130
	v_cmp_gt_i32_e64 s[50:51], 42, v130
	v_cmp_gt_i32_e64 s[52:53], 43, v130
	v_cndmask_b32_e64 v100, v100, v181, s[38:39]
	v_cndmask_b32_e64 v101, v101, v181, s[40:41]
	v_cndmask_b32_e64 v102, v102, v181, s[42:43]
	v_cndmask_b32_e64 v103, v103, v181, s[44:45]
	v_cndmask_b32_e64 v104, v104, v181, s[46:47]
	v_cndmask_b32_e64 v105, v105, v181, s[48:49]
	v_cndmask_b32_e64 v106, v106, v181, s[50:51]
	v_cndmask_b32_e64 v107, v107, v181, s[52:53]
	v_cmp_gt_i32_e64 s[38:39], 48, v130
	v_cmp_gt_i32_e64 s[40:41], 49, v130
	v_cmp_gt_i32_e64 s[42:43], 50, v130
	v_cmp_gt_i32_e64 s[44:45], 51, v130
	v_cmp_gt_i32_e64 s[46:47], 56, v130
	v_cmp_gt_i32_e64 s[48:49], 57, v130
	v_cmp_gt_i32_e64 s[50:51], 58, v130
	v_cmp_gt_i32_e64 s[52:53], 59, v130
	v_cndmask_b32_e64 v108, v108, v181, s[38:39]
	v_cndmask_b32_e64 v109, v109, v181, s[40:41]
	v_cndmask_b32_e64 v110, v110, v181, s[42:43]
	v_cndmask_b32_e64 v111, v111, v181, s[44:45]
	v_cndmask_b32_e64 v112, v112, v181, s[46:47]
	v_cndmask_b32_e64 v113, v113, v181, s[48:49]
	v_cndmask_b32_e64 v114, v114, v181, s[50:51]
	v_cndmask_b32_e64 v115, v115, v181, s[52:53]
; #define LAS __attribute__((address_space(3)))
; __device__ __forceinline__ unsigned pkhw(float lo, float hi) { f32x2q v = {lo, hi}; bf16x2q b = __builtin_convertvector(v, bf16x2q); return __builtin_bit_cast(unsigned, b); }
; __device__ __forceinline__ void mla_unit(const Ctx& C, const Params& p, int unit) {
;     ...
;                 float mx = fmaxf(s[g][0][0], s[g][0][1]);
;                 mx = fmaxf(fmaxf(mx, s[g][0][2]), s[g][0][3]);
; #pragma unroll
;                 for (int blk = 1; blk < 4; ++blk) { mx = fmaxf(fmaxf(mx, s[g][blk][0]), s[g][blk][1]); mx = fmaxf(fmaxf(mx, s[g][blk][2]), s[g][blk][3]); }
;                 mx = rowmax4(mx);
;                 const float mn = fmaxf(m[g], mx * c2), alpha = __builtin_amdgcn_exp2f(m[g] - mn); m[g] = mn;
;                 f32x2 ps2 = (f32x2){0.f, 0.f};
;                 const f32x2 c2v = (f32x2){c2, c2}, mnv = (f32x2){mn, mn};
; #pragma unroll
;                 for (int blk = 0; blk < 4; ++blk)
; #pragma unroll
;                     for (int jp = 0; jp < 2; ++jp) { f32x2 x = (f32x2){s[g][blk][2 * jp], s[g][blk][2 * jp + 1]}; x = x * c2v - mnv;
;                         f32x2 pv; pv.x = __builtin_amdgcn_exp2f(x.x); pv.y = __builtin_amdgcn_exp2f(x.y); ps2 = ps2 + pv; s[g][blk][2 * jp] = pv.x; s[g][blk][2 * jp + 1] = pv.y; }
;                 const float ps = ps2.x + ps2.y;
;                 lsum[g] = lsum[g] * alpha + ps;
;                 if (__builtin_amdgcn_ballot_w64(alpha != 1.0f) != 0ull) {
; #pragma unroll
;                     for (int d = 0; d < 4; ++d) o[g][d] = o[g][d] * alpha;
;                 }
; #pragma unroll
;                 for (int hf = 0; hf < 2; ++hf) { v4u pw; pw.x = pkhw(s[g][2 * hf][0], s[g][2 * hf][1]); pw.y = pkhw(s[g][2 * hf][2], s[g][2 * hf][3]); pw.z = pkhw(s[g][2 * hf + 1][0], s[g][2 * hf + 1][1]); pw.w = pkhw(s[g][2 * hf + 1][2], s[g][2 * hf + 1][3]);
;                     pf[g][hf] = __builtin_bit_cast(bf16x8, pw); }
;             }
; #pragma unroll
;             for (int hf = 0; hf < 2; ++hf)
; #pragma unroll
;                 for (int d = 0; d < 4; ++d) {
;                     const bf16x8 vf = *(const LAS bf16x8*)(Vb + (d * 16 + fr) * AV_ROW + (hf * 32 + fq * 8) * 2);
; #pragma unroll
;                     for (int g = 0; g < 2; ++g) o[g][d] = __builtin_amdgcn_mfma_f32_16x16x32_bf16(vf, pf[g][hf], o[g][d], 0, 0, 0);
;                 }
.Lmla_nomask:
	v_max3_f32 v130, v84, v85, v86
	v_max3_f32 v131, v100, v101, v102
	v_max3_f32 v130, v130, v87, v88
	v_max3_f32 v131, v131, v103, v104
	v_max3_f32 v130, v130, v89, v90
	v_max3_f32 v131, v131, v105, v106
	v_max3_f32 v130, v130, v91, v92
	v_max3_f32 v131, v131, v107, v108
	v_max3_f32 v130, v130, v93, v94
	v_max3_f32 v131, v131, v109, v110
	v_max3_f32 v130, v130, v95, v96
	v_max3_f32 v131, v131, v111, v112
	v_max3_f32 v130, v130, v97, v98
	v_max3_f32 v131, v131, v113, v114
	v_max_f32_e32 v130, v130, v99
	v_max_f32_e32 v131, v131, v115
	v_max_f32_e32 v130, v130, v131
	v_mov_b32_e32 v131, v130
	s_nop 1
	v_permlane32_swap_b32_e32 v130, v131
	v_max_f32_e32 v130, v130, v131
	v_mul_f32_e32 v130, 0x3e16c740, v130
	v_max_f32_e32 v2, v152, v130
	v_sub_f32_e32 v130, v152, v2
	v_exp_f32_e32 v152, v130
	v_pk_fma_f32 v[84:85], v[84:85], s[60:61], v[2:3] op_sel_hi:[1,0,0] neg_lo:[0,0,1] neg_hi:[0,0,1]
	v_pk_fma_f32 v[86:87], v[86:87], s[60:61], v[2:3] op_sel_hi:[1,0,0] neg_lo:[0,0,1] neg_hi:[0,0,1]
	v_cmp_neq_f32_e32 vcc, 1.0, v152
	v_pk_fma_f32 v[88:89], v[88:89], s[60:61], v[2:3] op_sel_hi:[1,0,0] neg_lo:[0,0,1] neg_hi:[0,0,1]
	v_pk_fma_f32 v[90:91], v[90:91], s[60:61], v[2:3] op_sel_hi:[1,0,0] neg_lo:[0,0,1] neg_hi:[0,0,1]
	v_pk_fma_f32 v[92:93], v[92:93], s[60:61], v[2:3] op_sel_hi:[1,0,0] neg_lo:[0,0,1] neg_hi:[0,0,1]
	v_pk_fma_f32 v[94:95], v[94:95], s[60:61], v[2:3] op_sel_hi:[1,0,0] neg_lo:[0,0,1] neg_hi:[0,0,1]
	v_pk_fma_f32 v[96:97], v[96:97], s[60:61], v[2:3] op_sel_hi:[1,0,0] neg_lo:[0,0,1] neg_hi:[0,0,1]
	v_pk_fma_f32 v[98:99], v[98:99], s[60:61], v[2:3] op_sel_hi:[1,0,0] neg_lo:[0,0,1] neg_hi:[0,0,1]
	s_cbranch_vccz .Lmla_norescale
	v_pk_mul_f32 v[64:65], v[64:65], v[152:153] op_sel_hi:[1,0]
	v_pk_mul_f32 v[66:67], v[66:67], v[152:153] op_sel_hi:[1,0]
	v_pk_mul_f32 v[68:69], v[68:69], v[152:153] op_sel_hi:[1,0]
	v_pk_mul_f32 v[70:71], v[70:71], v[152:153] op_sel_hi:[1,0]
	v_pk_mul_f32 v[72:73], v[72:73], v[152:153] op_sel_hi:[1,0]
	v_pk_mul_f32 v[74:75], v[74:75], v[152:153] op_sel_hi:[1,0]
	v_pk_mul_f32 v[76:77], v[76:77], v[152:153] op_sel_hi:[1,0]
	v_pk_mul_f32 v[78:79], v[78:79], v[152:153] op_sel_hi:[1,0]
	v_pk_mul_f32 v[48:49], v[48:49], v[152:153] op_sel_hi:[1,0]
	v_pk_mul_f32 v[50:51], v[50:51], v[152:153] op_sel_hi:[1,0]
	v_pk_mul_f32 v[52:53], v[52:53], v[152:153] op_sel_hi:[1,0]
	v_pk_mul_f32 v[54:55], v[54:55], v[152:153] op_sel_hi:[1,0]
	v_pk_mul_f32 v[56:57], v[56:57], v[152:153] op_sel_hi:[1,0]
	v_pk_mul_f32 v[58:59], v[58:59], v[152:153] op_sel_hi:[1,0]
	v_pk_mul_f32 v[60:61], v[60:61], v[152:153] op_sel_hi:[1,0]
	v_pk_mul_f32 v[62:63], v[62:63], v[152:153] op_sel_hi:[1,0]
.Lmla_norescale:
	v_exp_f32_e32 v84, v84
	v_exp_f32_e32 v85, v85
	v_exp_f32_e32 v86, v86
	v_exp_f32_e32 v87, v87
	v_exp_f32_e32 v88, v88
	v_exp_f32_e32 v89, v89
	v_exp_f32_e32 v90, v90
	v_exp_f32_e32 v91, v91
	v_exp_f32_e32 v92, v92
	v_exp_f32_e32 v93, v93
	v_exp_f32_e32 v94, v94
	v_exp_f32_e32 v95, v95
	v_exp_f32_e32 v96, v96
	v_exp_f32_e32 v97, v97
	v_exp_f32_e32 v98, v98
	v_exp_f32_e32 v99, v99
	v_pk_add_f32 v[130:131], v[84:85], v[86:87]
	v_pk_add_f32 v[132:133], v[88:89], v[90:91]
	v_pk_add_f32 v[130:131], v[130:131], v[92:93]
	v_pk_add_f32 v[132:133], v[132:133], v[94:95]
	v_pk_add_f32 v[130:131], v[130:131], v[96:97]
	v_pk_add_f32 v[132:133], v[132:133], v[98:99]
	v_cvt_pk_bf16_f32 v84, v84, v85
	v_cvt_pk_bf16_f32 v85, v86, v87
	v_cvt_pk_bf16_f32 v86, v88, v89
	v_cvt_pk_bf16_f32 v87, v90, v91
	v_cvt_pk_bf16_f32 v92, v92, v93
	v_cvt_pk_bf16_f32 v93, v94, v95
	v_cvt_pk_bf16_f32 v94, v96, v97
	v_cvt_pk_bf16_f32 v95, v98, v99
	s_waitcnt lgkmcnt(4)
	v_mfma_f32_32x32x16_bf16 v[64:79], v[198:201], v[84:87], v[64:79]
	v_pk_fma_f32 v[100:101], v[100:101], s[60:61], v[2:3] op_sel_hi:[1,0,0] neg_lo:[0,0,1] neg_hi:[0,0,1]
	v_pk_fma_f32 v[102:103], v[102:103], s[60:61], v[2:3] op_sel_hi:[1,0,0] neg_lo:[0,0,1] neg_hi:[0,0,1]
	v_pk_fma_f32 v[104:105], v[104:105], s[60:61], v[2:3] op_sel_hi:[1,0,0] neg_lo:[0,0,1] neg_hi:[0,0,1]
	v_pk_fma_f32 v[106:107], v[106:107], s[60:61], v[2:3] op_sel_hi:[1,0,0] neg_lo:[0,0,1] neg_hi:[0,0,1]
	v_pk_fma_f32 v[108:109], v[108:109], s[60:61], v[2:3] op_sel_hi:[1,0,0] neg_lo:[0,0,1] neg_hi:[0,0,1]
	v_pk_fma_f32 v[110:111], v[110:111], s[60:61], v[2:3] op_sel_hi:[1,0,0] neg_lo:[0,0,1] neg_hi:[0,0,1]
	v_pk_fma_f32 v[112:113], v[112:113], s[60:61], v[2:3] op_sel_hi:[1,0,0] neg_lo:[0,0,1] neg_hi:[0,0,1]
	v_pk_fma_f32 v[114:115], v[114:115], s[60:61], v[2:3] op_sel_hi:[1,0,0] neg_lo:[0,0,1] neg_hi:[0,0,1]
	v_exp_f32_e32 v100, v100
	v_exp_f32_e32 v101, v101
	v_exp_f32_e32 v102, v102
	v_mfma_f32_32x32x16_bf16 v[48:63], v[202:205], v[84:87], v[48:63]
	v_exp_f32_e32 v103, v103
	v_exp_f32_e32 v104, v104
	v_exp_f32_e32 v105, v105
	v_exp_f32_e32 v106, v106
	v_exp_f32_e32 v107, v107
	v_exp_f32_e32 v108, v108
	v_exp_f32_e32 v109, v109
	v_exp_f32_e32 v110, v110
	v_exp_f32_e32 v111, v111
	v_exp_f32_e32 v112, v112
	v_exp_f32_e32 v113, v113
	v_mfma_f32_32x32x16_bf16 v[64:79], v[206:209], v[92:95], v[64:79]
	v_exp_f32_e32 v114, v114
	v_exp_f32_e32 v115, v115
	v_pk_add_f32 v[130:131], v[130:131], v[100:101]
	v_pk_add_f32 v[132:133], v[132:133], v[102:103]
	v_pk_add_f32 v[130:131], v[130:131], v[104:105]
	v_pk_add_f32 v[132:133], v[132:133], v[106:107]
	v_pk_add_f32 v[130:131], v[130:131], v[108:109]
	v_pk_add_f32 v[132:133], v[132:133], v[110:111]
	v_pk_add_f32 v[130:131], v[130:131], v[112:113]
	v_pk_add_f32 v[132:133], v[132:133], v[114:115]
	v_pk_add_f32 v[130:131], v[130:131], v[132:133]
	v_mfma_f32_32x32x16_bf16 v[48:63], v[210:213], v[92:95], v[48:63]
	v_add_f32_e32 v130, v130, v131
	v_fma_f32 v190, v190, v152, v130
	v_cvt_pk_bf16_f32 v100, v100, v101
	v_cvt_pk_bf16_f32 v101, v102, v103
	v_cvt_pk_bf16_f32 v102, v104, v105
	v_cvt_pk_bf16_f32 v103, v106, v107
	v_cvt_pk_bf16_f32 v108, v108, v109
	v_cvt_pk_bf16_f32 v109, v110, v111
	v_cvt_pk_bf16_f32 v110, v112, v113
	v_cvt_pk_bf16_f32 v111, v114, v115
	s_waitcnt lgkmcnt(0)
	v_mfma_f32_32x32x16_bf16 v[64:79], v[214:217], v[100:103], v[64:79]
	v_mfma_f32_32x32x16_bf16 v[48:63], v[218:221], v[100:103], v[48:63]
	v_mfma_f32_32x32x16_bf16 v[64:79], v[222:225], v[108:111], v[64:79]
	v_mfma_f32_32x32x16_bf16 v[48:63], v[226:229], v[108:111], v[48:63]
